# P4/P8 epilogues (whole tiles and split-K partial slabs): bf16 stores lane-permuted like P6; on top of v9
# speedup vs baseline: 1.0059x; 1.0059x over previous
.LBB0_597:
	v_and_b32_e32 v165, 3, v174
	v_lshrrev_b32_e32 v170, 2, v174
	v_lshlrev_b32_e32 v164, 6, v165
	v_and_or_b32 v164, v174, 60, v164
	v_and_b32_e32 v171, 15, v174
	v_sub_u32_e32 v170, v170, v171
	v_lshrrev_b32_e32 v171, 4, v174
	v_sub_u32_e32 v165, v165, v171
	v_mul_i32_i24_e32 v170, 0x200, v170
	v_lshl_add_u32 v166, v165, 4, v170
	v_ashrrev_i32_e32 v167, 31, v166
	s_add_i32 s2, s2, -1
	s_lshl_b64 s[28:29], s[2:3], 17
	v_lshl_add_u64 v[148:149], v[140:141], 0, s[28:29]
	v_cvt_pk_bf16_f32 v152, v126, v127
	v_cvt_pk_bf16_f32 v153, v128, v129
	v_cvt_pk_bf16_f32 v154, v122, v123
	v_cvt_pk_bf16_f32 v155, v124, v125
	s_movk_i32 s2, 0x2000
	ds_bpermute_b32 v152, v164, v152
	ds_bpermute_b32 v153, v164, v153
	ds_bpermute_b32 v154, v164, v154
	ds_bpermute_b32 v155, v164, v155
	v_lshl_add_u64 v[168:169], v[166:167], 0, v[148:149]
	s_waitcnt lgkmcnt(0)
	global_store_dwordx4 v[168:169], v[152:155], off
	v_add_co_u32_e32 v156, vcc, s2, v148
	s_nop 0
	v_cvt_pk_bf16_f32 v152, v118, v119
	v_cvt_pk_bf16_f32 v153, v120, v121
	v_cvt_pk_bf16_f32 v154, v114, v115
	v_cvt_pk_bf16_f32 v155, v116, v117
	ds_bpermute_b32 v152, v164, v152
	ds_bpermute_b32 v153, v164, v153
	ds_bpermute_b32 v154, v164, v154
	ds_bpermute_b32 v155, v164, v155
	v_lshl_add_u64 v[168:169], v[166:167], 0, v[148:149]
	s_waitcnt lgkmcnt(0)
	global_store_dwordx4 v[168:169], v[152:155], off offset:256
	v_addc_co_u32_e32 v157, vcc, 0, v149, vcc
	s_nop 0
	v_cvt_pk_bf16_f32 v152, v110, v111
	v_cvt_pk_bf16_f32 v153, v112, v113
	v_cvt_pk_bf16_f32 v154, v106, v107
	v_cvt_pk_bf16_f32 v155, v108, v109
	s_movk_i32 s2, 0x4000
	ds_bpermute_b32 v152, v164, v152
	ds_bpermute_b32 v153, v164, v153
	ds_bpermute_b32 v154, v164, v154
	ds_bpermute_b32 v155, v164, v155
	v_lshl_add_u64 v[168:169], v[166:167], 0, v[156:157]
	s_waitcnt lgkmcnt(0)
	global_store_dwordx4 v[168:169], v[152:155], off
	s_mov_b64 s[28:29], 0
	s_nop 0
	v_cvt_pk_bf16_f32 v152, v102, v103
	v_cvt_pk_bf16_f32 v153, v104, v105
	v_cvt_pk_bf16_f32 v154, v98, v99
	v_cvt_pk_bf16_f32 v155, v100, v101
	ds_bpermute_b32 v152, v164, v152
	ds_bpermute_b32 v153, v164, v153
	ds_bpermute_b32 v154, v164, v154
	ds_bpermute_b32 v155, v164, v155
	v_lshl_add_u64 v[168:169], v[166:167], 0, v[156:157]
	s_waitcnt lgkmcnt(0)
	global_store_dwordx4 v[168:169], v[152:155], off offset:256
	v_add_co_u32_e32 v156, vcc, s2, v148
	s_nop 0
	v_cvt_pk_bf16_f32 v152, v94, v95
	v_cvt_pk_bf16_f32 v153, v96, v97
	v_cvt_pk_bf16_f32 v154, v90, v91
	v_cvt_pk_bf16_f32 v155, v92, v93
	s_nop 0
	v_addc_co_u32_e32 v157, vcc, 0, v149, vcc
	s_movk_i32 s2, 0x6000
	ds_bpermute_b32 v152, v164, v152
	ds_bpermute_b32 v153, v164, v153
	ds_bpermute_b32 v154, v164, v154
	ds_bpermute_b32 v155, v164, v155
	v_lshl_add_u64 v[168:169], v[166:167], 0, v[156:157]
	s_waitcnt lgkmcnt(0)
	global_store_dwordx4 v[168:169], v[152:155], off
	s_nop 1
	v_cvt_pk_bf16_f32 v152, v86, v87
	v_cvt_pk_bf16_f32 v153, v88, v89
	v_cvt_pk_bf16_f32 v154, v82, v83
	v_cvt_pk_bf16_f32 v155, v84, v85
	ds_bpermute_b32 v152, v164, v152
	ds_bpermute_b32 v153, v164, v153
	ds_bpermute_b32 v154, v164, v154
	ds_bpermute_b32 v155, v164, v155
	v_lshl_add_u64 v[168:169], v[166:167], 0, v[156:157]
	s_waitcnt lgkmcnt(0)
	global_store_dwordx4 v[168:169], v[152:155], off offset:256
	v_add_co_u32_e32 v156, vcc, s2, v148
	s_nop 0
	v_cvt_pk_bf16_f32 v152, v78, v79
	v_cvt_pk_bf16_f32 v153, v80, v81
	v_cvt_pk_bf16_f32 v154, v74, v75
	v_cvt_pk_bf16_f32 v155, v76, v77
	s_nop 0
	v_addc_co_u32_e32 v157, vcc, 0, v149, vcc
	s_mov_b32 s2, 0x10000
	ds_bpermute_b32 v152, v164, v152
	ds_bpermute_b32 v153, v164, v153
	ds_bpermute_b32 v154, v164, v154
	ds_bpermute_b32 v155, v164, v155
	v_lshl_add_u64 v[168:169], v[166:167], 0, v[156:157]
	s_waitcnt lgkmcnt(0)
	global_store_dwordx4 v[168:169], v[152:155], off
	s_nop 1
	v_cvt_pk_bf16_f32 v152, v70, v71
	v_cvt_pk_bf16_f32 v153, v72, v73
	v_cvt_pk_bf16_f32 v154, v66, v67
	v_cvt_pk_bf16_f32 v155, v68, v69
	ds_bpermute_b32 v152, v164, v152
	ds_bpermute_b32 v153, v164, v153
	ds_bpermute_b32 v154, v164, v154
	ds_bpermute_b32 v155, v164, v155
	v_lshl_add_u64 v[168:169], v[166:167], 0, v[156:157]
	s_waitcnt lgkmcnt(0)
	global_store_dwordx4 v[168:169], v[152:155], off offset:256
	v_add_co_u32_e32 v156, vcc, s2, v148
	s_nop 0
	v_cvt_pk_bf16_f32 v152, v62, v63
	v_cvt_pk_bf16_f32 v153, v64, v65
	v_cvt_pk_bf16_f32 v154, v58, v59
	v_cvt_pk_bf16_f32 v155, v60, v61
	s_nop 0
	v_addc_co_u32_e32 v157, vcc, 0, v149, vcc
	s_mov_b32 s2, 0x12000
	ds_bpermute_b32 v152, v164, v152
	ds_bpermute_b32 v153, v164, v153
	ds_bpermute_b32 v154, v164, v154
	ds_bpermute_b32 v155, v164, v155
	v_lshl_add_u64 v[168:169], v[166:167], 0, v[156:157]
	s_waitcnt lgkmcnt(0)
	global_store_dwordx4 v[168:169], v[152:155], off
	s_nop 1
	v_cvt_pk_bf16_f32 v152, v54, v55
	v_cvt_pk_bf16_f32 v153, v56, v57
	v_cvt_pk_bf16_f32 v154, v50, v51
	v_cvt_pk_bf16_f32 v155, v52, v53
	ds_bpermute_b32 v152, v164, v152
	ds_bpermute_b32 v153, v164, v153
	ds_bpermute_b32 v154, v164, v154
	ds_bpermute_b32 v155, v164, v155
	v_lshl_add_u64 v[168:169], v[166:167], 0, v[156:157]
	s_waitcnt lgkmcnt(0)
	global_store_dwordx4 v[168:169], v[152:155], off offset:256
	v_add_co_u32_e32 v156, vcc, s2, v148
	s_nop 0
	v_cvt_pk_bf16_f32 v152, v46, v47
	v_cvt_pk_bf16_f32 v153, v48, v49
	v_cvt_pk_bf16_f32 v154, v42, v43
	v_cvt_pk_bf16_f32 v155, v44, v45
	s_nop 0
	v_addc_co_u32_e32 v157, vcc, 0, v149, vcc
	s_mov_b32 s2, 0x14000
	ds_bpermute_b32 v152, v164, v152
	ds_bpermute_b32 v153, v164, v153
	ds_bpermute_b32 v154, v164, v154
	ds_bpermute_b32 v155, v164, v155
	v_lshl_add_u64 v[168:169], v[166:167], 0, v[156:157]
	s_waitcnt lgkmcnt(0)
	global_store_dwordx4 v[168:169], v[152:155], off
	s_nop 1
	v_cvt_pk_bf16_f32 v152, v38, v39
	v_cvt_pk_bf16_f32 v153, v40, v41
	v_cvt_pk_bf16_f32 v154, v34, v35
	v_cvt_pk_bf16_f32 v155, v36, v37
	ds_bpermute_b32 v152, v164, v152
	ds_bpermute_b32 v153, v164, v153
	ds_bpermute_b32 v154, v164, v154
	ds_bpermute_b32 v155, v164, v155
	v_lshl_add_u64 v[168:169], v[166:167], 0, v[156:157]
	s_waitcnt lgkmcnt(0)
	global_store_dwordx4 v[168:169], v[152:155], off offset:256
	v_add_co_u32_e32 v156, vcc, s2, v148
	s_nop 0
	v_cvt_pk_bf16_f32 v152, v30, v31
	v_cvt_pk_bf16_f32 v153, v32, v33
	v_cvt_pk_bf16_f32 v154, v26, v27
	v_cvt_pk_bf16_f32 v155, v28, v29
	s_nop 0
	v_addc_co_u32_e32 v157, vcc, 0, v149, vcc
	s_mov_b32 s2, 0x16000
	ds_bpermute_b32 v152, v164, v152
	ds_bpermute_b32 v153, v164, v153
	ds_bpermute_b32 v154, v164, v154
	ds_bpermute_b32 v155, v164, v155
	v_lshl_add_u64 v[168:169], v[166:167], 0, v[156:157]
	s_waitcnt lgkmcnt(0)
	global_store_dwordx4 v[168:169], v[152:155], off
	v_add_co_u32_e32 v148, vcc, s2, v148
	s_nop 0
	v_cvt_pk_bf16_f32 v152, v22, v23
	v_cvt_pk_bf16_f32 v153, v24, v25
	v_cvt_pk_bf16_f32 v154, v18, v19
	v_cvt_pk_bf16_f32 v155, v20, v21
	ds_bpermute_b32 v152, v164, v152
	ds_bpermute_b32 v153, v164, v153
	ds_bpermute_b32 v154, v164, v154
	ds_bpermute_b32 v155, v164, v155
	v_lshl_add_u64 v[168:169], v[166:167], 0, v[156:157]
	s_waitcnt lgkmcnt(0)
	global_store_dwordx4 v[168:169], v[152:155], off offset:256
	v_addc_co_u32_e32 v149, vcc, 0, v149, vcc
	s_nop 0
	v_cvt_pk_bf16_f32 v152, v14, v15
	v_cvt_pk_bf16_f32 v153, v16, v17
	v_cvt_pk_bf16_f32 v154, v10, v11
	v_cvt_pk_bf16_f32 v155, v12, v13
	ds_bpermute_b32 v152, v164, v152
	ds_bpermute_b32 v153, v164, v153
	ds_bpermute_b32 v154, v164, v154
	ds_bpermute_b32 v155, v164, v155
	v_lshl_add_u64 v[168:169], v[166:167], 0, v[148:149]
	s_waitcnt lgkmcnt(0)
	global_store_dwordx4 v[168:169], v[152:155], off
	s_nop 1
	v_cvt_pk_bf16_f32 v152, v6, v7
	v_cvt_pk_bf16_f32 v153, v8, v9
	v_cvt_pk_bf16_f32 v154, v2, v3
	v_cvt_pk_bf16_f32 v155, v4, v5
	ds_bpermute_b32 v152, v164, v152
	ds_bpermute_b32 v153, v164, v153
	ds_bpermute_b32 v154, v164, v154
	ds_bpermute_b32 v155, v164, v155
	v_lshl_add_u64 v[168:169], v[166:167], 0, v[148:149]
	s_waitcnt lgkmcnt(0)
	global_store_dwordx4 v[168:169], v[152:155], off offset:256
.LBB0_598:
	s_andn2_b64 vcc, exec, s[28:29]
	s_cbranch_vccnz .LBB0_588
	v_and_b32_e32 v165, 3, v174
	v_lshrrev_b32_e32 v170, 2, v174
	v_lshlrev_b32_e32 v164, 6, v165
	v_and_or_b32 v164, v174, 60, v164
	v_and_b32_e32 v171, 15, v174
	v_sub_u32_e32 v170, v170, v171
	v_lshrrev_b32_e32 v171, 4, v174
	v_sub_u32_e32 v165, v165, v171
	v_mul_i32_i24_e32 v170, 0x2000, v170
	v_lshl_add_u32 v166, v165, 4, v170
	v_ashrrev_i32_e32 v167, 31, v166
	v_lshl_add_u32 v152, s18, 8, v138
	v_lshl_or_b32 v148, s16, 8, v139
	v_ashrrev_i32_e32 v153, 31, v152
	v_ashrrev_i32_e32 v149, 31, v148
	v_lshlrev_b64 v[154:155], 13, v[152:153]
	v_lshl_add_u64 v[154:155], s[4:5], 0, v[154:155]
	v_lshlrev_b64 v[156:157], 1, v[148:149]
	v_lshl_add_u64 v[148:149], v[154:155], 0, v[156:157]
	v_cvt_pk_bf16_f32 v126, v126, v127
	v_cvt_pk_bf16_f32 v127, v128, v129
	v_cvt_pk_bf16_f32 v128, v122, v123
	v_cvt_pk_bf16_f32 v129, v124, v125
	ds_bpermute_b32 v126, v164, v126
	ds_bpermute_b32 v127, v164, v127
	ds_bpermute_b32 v128, v164, v128
	ds_bpermute_b32 v129, v164, v129
	v_lshl_add_u64 v[168:169], v[166:167], 0, v[148:149]
	s_waitcnt lgkmcnt(0)
	global_store_dwordx4 v[168:169], v[126:129], off
	v_cvt_pk_bf16_f32 v118, v118, v119
	v_cvt_pk_bf16_f32 v119, v120, v121
	v_cvt_pk_bf16_f32 v120, v114, v115
	v_or_b32_e32 v114, 16, v152
	v_ashrrev_i32_e32 v115, 31, v114
	v_lshlrev_b64 v[114:115], 13, v[114:115]
	v_lshl_add_u64 v[114:115], s[4:5], 0, v[114:115]
	v_lshl_add_u64 v[114:115], v[114:115], 0, v[156:157]
	v_cvt_pk_bf16_f32 v121, v116, v117
	ds_bpermute_b32 v118, v164, v118
	ds_bpermute_b32 v119, v164, v119
	ds_bpermute_b32 v120, v164, v120
	ds_bpermute_b32 v121, v164, v121
	v_lshl_add_u64 v[168:169], v[166:167], 0, v[148:149]
	s_waitcnt lgkmcnt(0)
	global_store_dwordx4 v[168:169], v[118:121], off offset:256
	v_cvt_pk_bf16_f32 v110, v110, v111
	v_cvt_pk_bf16_f32 v111, v112, v113
	v_cvt_pk_bf16_f32 v112, v106, v107
	v_cvt_pk_bf16_f32 v113, v108, v109
	ds_bpermute_b32 v110, v164, v110
	ds_bpermute_b32 v111, v164, v111
	ds_bpermute_b32 v112, v164, v112
	ds_bpermute_b32 v113, v164, v113
	v_lshl_add_u64 v[168:169], v[166:167], 0, v[114:115]
	s_waitcnt lgkmcnt(0)
	global_store_dwordx4 v[168:169], v[110:113], off
	v_cvt_pk_bf16_f32 v102, v102, v103
	v_cvt_pk_bf16_f32 v103, v104, v105
	v_cvt_pk_bf16_f32 v104, v98, v99
	v_or_b32_e32 v98, 32, v152
	v_ashrrev_i32_e32 v99, 31, v98
	v_lshlrev_b64 v[98:99], 13, v[98:99]
	v_lshl_add_u64 v[98:99], s[4:5], 0, v[98:99]
	v_lshl_add_u64 v[98:99], v[98:99], 0, v[156:157]
	v_cvt_pk_bf16_f32 v105, v100, v101
	ds_bpermute_b32 v102, v164, v102
	ds_bpermute_b32 v103, v164, v103
	ds_bpermute_b32 v104, v164, v104
	ds_bpermute_b32 v105, v164, v105
	v_lshl_add_u64 v[168:169], v[166:167], 0, v[114:115]
	s_waitcnt lgkmcnt(0)
	global_store_dwordx4 v[168:169], v[102:105], off offset:256
	v_cvt_pk_bf16_f32 v94, v94, v95
	v_cvt_pk_bf16_f32 v95, v96, v97
	v_cvt_pk_bf16_f32 v96, v90, v91
	v_cvt_pk_bf16_f32 v97, v92, v93
	ds_bpermute_b32 v94, v164, v94
	ds_bpermute_b32 v95, v164, v95
	ds_bpermute_b32 v96, v164, v96
	ds_bpermute_b32 v97, v164, v97
	v_lshl_add_u64 v[168:169], v[166:167], 0, v[98:99]
	s_waitcnt lgkmcnt(0)
	global_store_dwordx4 v[168:169], v[94:97], off
	v_cvt_pk_bf16_f32 v86, v86, v87
	v_cvt_pk_bf16_f32 v87, v88, v89
	v_cvt_pk_bf16_f32 v88, v82, v83
	v_or_b32_e32 v82, 48, v152
	v_ashrrev_i32_e32 v83, 31, v82
	v_lshlrev_b64 v[82:83], 13, v[82:83]
	v_lshl_add_u64 v[82:83], s[4:5], 0, v[82:83]
	v_lshl_add_u64 v[82:83], v[82:83], 0, v[156:157]
	s_mov_b32 s2, 0x100000
	v_cvt_pk_bf16_f32 v89, v84, v85
	ds_bpermute_b32 v86, v164, v86
	ds_bpermute_b32 v87, v164, v87
	ds_bpermute_b32 v88, v164, v88
	ds_bpermute_b32 v89, v164, v89
	v_lshl_add_u64 v[168:169], v[166:167], 0, v[98:99]
	s_waitcnt lgkmcnt(0)
	global_store_dwordx4 v[168:169], v[86:89], off offset:256
	v_cvt_pk_bf16_f32 v78, v78, v79
	v_cvt_pk_bf16_f32 v79, v80, v81
	v_cvt_pk_bf16_f32 v80, v74, v75
	v_cvt_pk_bf16_f32 v81, v76, v77
	ds_bpermute_b32 v78, v164, v78
	ds_bpermute_b32 v79, v164, v79
	ds_bpermute_b32 v80, v164, v80
	ds_bpermute_b32 v81, v164, v81
	v_lshl_add_u64 v[168:169], v[166:167], 0, v[82:83]
	s_waitcnt lgkmcnt(0)
	global_store_dwordx4 v[168:169], v[78:81], off
	v_cvt_pk_bf16_f32 v70, v70, v71
	v_cvt_pk_bf16_f32 v71, v72, v73
	v_cvt_pk_bf16_f32 v72, v66, v67
	v_cvt_pk_bf16_f32 v73, v68, v69
	ds_bpermute_b32 v70, v164, v70
	ds_bpermute_b32 v71, v164, v71
	ds_bpermute_b32 v72, v164, v72
	ds_bpermute_b32 v73, v164, v73
	v_lshl_add_u64 v[168:169], v[166:167], 0, v[82:83]
	s_waitcnt lgkmcnt(0)
	global_store_dwordx4 v[168:169], v[70:73], off offset:256
	s_mov_b64 s[28:29], 0x100000
	v_cvt_pk_bf16_f32 v62, v62, v63
	v_cvt_pk_bf16_f32 v63, v64, v65
	v_cvt_pk_bf16_f32 v64, v58, v59
	v_add_co_u32_e32 v58, vcc, s2, v148
	v_lshl_add_u64 v[66:67], v[148:149], 0, s[28:29]
	s_nop 0
	v_addc_co_u32_e32 v59, vcc, 0, v149, vcc
	v_cvt_pk_bf16_f32 v65, v60, v61
	ds_bpermute_b32 v62, v164, v62
	ds_bpermute_b32 v63, v164, v63
	ds_bpermute_b32 v64, v164, v64
	ds_bpermute_b32 v65, v164, v65
	v_lshl_add_u64 v[168:169], v[166:167], 0, v[58:59]
	s_waitcnt lgkmcnt(0)
	global_store_dwordx4 v[168:169], v[62:65], off
	v_cvt_pk_bf16_f32 v54, v54, v55
	v_cvt_pk_bf16_f32 v55, v56, v57
	v_cvt_pk_bf16_f32 v56, v50, v51
	v_cvt_pk_bf16_f32 v57, v52, v53
	ds_bpermute_b32 v54, v164, v54
	ds_bpermute_b32 v55, v164, v55
	ds_bpermute_b32 v56, v164, v56
	ds_bpermute_b32 v57, v164, v57
	v_lshl_add_u64 v[168:169], v[166:167], 0, v[66:67]
	s_waitcnt lgkmcnt(0)
	global_store_dwordx4 v[168:169], v[54:57], off offset:256
	v_cvt_pk_bf16_f32 v46, v46, v47
	v_cvt_pk_bf16_f32 v47, v48, v49
	v_cvt_pk_bf16_f32 v48, v42, v43
	v_add_co_u32_e32 v42, vcc, s55, v148
	v_lshl_add_u64 v[50:51], v[148:149], 0, s[8:9]
	s_nop 0
	v_addc_co_u32_e32 v43, vcc, 0, v149, vcc
	v_cvt_pk_bf16_f32 v49, v44, v45
	ds_bpermute_b32 v46, v164, v46
	ds_bpermute_b32 v47, v164, v47
	ds_bpermute_b32 v48, v164, v48
	ds_bpermute_b32 v49, v164, v49
	v_lshl_add_u64 v[168:169], v[166:167], 0, v[42:43]
	s_waitcnt lgkmcnt(0)
	global_store_dwordx4 v[168:169], v[46:49], off
	v_cvt_pk_bf16_f32 v38, v38, v39
	v_cvt_pk_bf16_f32 v39, v40, v41
	v_cvt_pk_bf16_f32 v40, v34, v35
	v_cvt_pk_bf16_f32 v41, v36, v37
	ds_bpermute_b32 v38, v164, v38
	ds_bpermute_b32 v39, v164, v39
	ds_bpermute_b32 v40, v164, v40
	ds_bpermute_b32 v41, v164, v41
	v_lshl_add_u64 v[168:169], v[166:167], 0, v[50:51]
	s_waitcnt lgkmcnt(0)
	global_store_dwordx4 v[168:169], v[38:41], off offset:256
	v_cvt_pk_bf16_f32 v30, v30, v31
	v_cvt_pk_bf16_f32 v31, v32, v33
	v_cvt_pk_bf16_f32 v32, v26, v27
	v_add_co_u32_e32 v26, vcc, s56, v148
	v_lshl_add_u64 v[34:35], v[148:149], 0, s[10:11]
	s_nop 0
	v_addc_co_u32_e32 v27, vcc, 0, v149, vcc
	v_cvt_pk_bf16_f32 v33, v28, v29
	ds_bpermute_b32 v30, v164, v30
	ds_bpermute_b32 v31, v164, v31
	ds_bpermute_b32 v32, v164, v32
	ds_bpermute_b32 v33, v164, v33
	v_lshl_add_u64 v[168:169], v[166:167], 0, v[26:27]
	s_waitcnt lgkmcnt(0)
	global_store_dwordx4 v[168:169], v[30:33], off
	v_cvt_pk_bf16_f32 v22, v22, v23
	v_cvt_pk_bf16_f32 v23, v24, v25
	v_cvt_pk_bf16_f32 v24, v18, v19
	v_cvt_pk_bf16_f32 v25, v20, v21
	ds_bpermute_b32 v22, v164, v22
	ds_bpermute_b32 v23, v164, v23
	ds_bpermute_b32 v24, v164, v24
	ds_bpermute_b32 v25, v164, v25
	v_lshl_add_u64 v[168:169], v[166:167], 0, v[34:35]
	s_waitcnt lgkmcnt(0)
	global_store_dwordx4 v[168:169], v[22:25], off offset:256
	v_cvt_pk_bf16_f32 v14, v14, v15
	v_cvt_pk_bf16_f32 v15, v16, v17
	v_cvt_pk_bf16_f32 v16, v10, v11
	v_add_co_u32_e32 v10, vcc, s57, v148
	v_lshl_add_u64 v[18:19], v[148:149], 0, s[12:13]
	s_nop 0
	v_addc_co_u32_e32 v11, vcc, 0, v149, vcc
	v_cvt_pk_bf16_f32 v17, v12, v13
	ds_bpermute_b32 v14, v164, v14
	ds_bpermute_b32 v15, v164, v15
	ds_bpermute_b32 v16, v164, v16
	ds_bpermute_b32 v17, v164, v17
	v_lshl_add_u64 v[168:169], v[166:167], 0, v[10:11]
	s_waitcnt lgkmcnt(0)
	global_store_dwordx4 v[168:169], v[14:17], off
	v_cvt_pk_bf16_f32 v6, v6, v7
	v_cvt_pk_bf16_f32 v7, v8, v9
	v_cvt_pk_bf16_f32 v8, v2, v3
	v_cvt_pk_bf16_f32 v9, v4, v5
	ds_bpermute_b32 v6, v164, v6
	ds_bpermute_b32 v7, v164, v7
	ds_bpermute_b32 v8, v164, v8
	ds_bpermute_b32 v9, v164, v9
	v_lshl_add_u64 v[168:169], v[166:167], 0, v[18:19]
	s_waitcnt lgkmcnt(0)
	global_store_dwordx4 v[168:169], v[6:9], off offset:256
	s_branch .LBB0_588

.LBB0_933:
	v_and_b32_e32 v165, 3, v174
	v_lshrrev_b32_e32 v170, 2, v174
	v_lshlrev_b32_e32 v164, 6, v165
	v_and_or_b32 v164, v174, 60, v164
	v_and_b32_e32 v171, 15, v174
	v_sub_u32_e32 v170, v170, v171
	v_lshrrev_b32_e32 v171, 4, v174
	v_sub_u32_e32 v165, v165, v171
	v_mul_i32_i24_e32 v170, 0x200, v170
	v_lshl_add_u32 v166, v165, 4, v170
	v_ashrrev_i32_e32 v167, 31, v166
	s_add_i32 s2, s2, -1
	s_lshl_b64 s[22:23], s[2:3], 17
	v_lshl_add_u64 v[150:151], v[142:143], 0, s[22:23]
	v_cvt_pk_bf16_f32 v154, v126, v127
	v_cvt_pk_bf16_f32 v155, v128, v129
	v_cvt_pk_bf16_f32 v156, v122, v123
	v_cvt_pk_bf16_f32 v157, v124, v125
	ds_bpermute_b32 v154, v164, v154
	ds_bpermute_b32 v155, v164, v155
	ds_bpermute_b32 v156, v164, v156
	ds_bpermute_b32 v157, v164, v157
	v_lshl_add_u64 v[168:169], v[166:167], 0, v[150:151]
	s_waitcnt lgkmcnt(0)
	global_store_dwordx4 v[168:169], v[154:157], off
	v_add_co_u32_e32 v158, vcc, s46, v150
	s_nop 0
	v_cvt_pk_bf16_f32 v154, v118, v119
	v_cvt_pk_bf16_f32 v155, v120, v121
	v_cvt_pk_bf16_f32 v156, v114, v115
	v_cvt_pk_bf16_f32 v157, v116, v117
	ds_bpermute_b32 v154, v164, v154
	ds_bpermute_b32 v155, v164, v155
	ds_bpermute_b32 v156, v164, v156
	ds_bpermute_b32 v157, v164, v157
	v_lshl_add_u64 v[168:169], v[166:167], 0, v[150:151]
	s_waitcnt lgkmcnt(0)
	global_store_dwordx4 v[168:169], v[154:157], off offset:256
	v_addc_co_u32_e32 v159, vcc, 0, v151, vcc
	s_nop 0
	v_cvt_pk_bf16_f32 v154, v110, v111
	v_cvt_pk_bf16_f32 v155, v112, v113
	v_cvt_pk_bf16_f32 v156, v106, v107
	v_cvt_pk_bf16_f32 v157, v108, v109
	ds_bpermute_b32 v154, v164, v154
	ds_bpermute_b32 v155, v164, v155
	ds_bpermute_b32 v156, v164, v156
	ds_bpermute_b32 v157, v164, v157
	v_lshl_add_u64 v[168:169], v[166:167], 0, v[158:159]
	s_waitcnt lgkmcnt(0)
	global_store_dwordx4 v[168:169], v[154:157], off
	s_mov_b64 s[22:23], 0
	s_nop 0
	v_cvt_pk_bf16_f32 v154, v102, v103
	v_cvt_pk_bf16_f32 v155, v104, v105
	v_cvt_pk_bf16_f32 v156, v98, v99
	v_cvt_pk_bf16_f32 v157, v100, v101
	ds_bpermute_b32 v154, v164, v154
	ds_bpermute_b32 v155, v164, v155
	ds_bpermute_b32 v156, v164, v156
	ds_bpermute_b32 v157, v164, v157
	v_lshl_add_u64 v[168:169], v[166:167], 0, v[158:159]
	s_waitcnt lgkmcnt(0)
	global_store_dwordx4 v[168:169], v[154:157], off offset:256
	v_add_co_u32_e32 v158, vcc, s47, v150
	s_nop 0
	v_cvt_pk_bf16_f32 v154, v94, v95
	v_cvt_pk_bf16_f32 v155, v96, v97
	v_cvt_pk_bf16_f32 v156, v90, v91
	v_cvt_pk_bf16_f32 v157, v92, v93
	s_nop 0
	v_addc_co_u32_e32 v159, vcc, 0, v151, vcc
	ds_bpermute_b32 v154, v164, v154
	ds_bpermute_b32 v155, v164, v155
	ds_bpermute_b32 v156, v164, v156
	ds_bpermute_b32 v157, v164, v157
	v_lshl_add_u64 v[168:169], v[166:167], 0, v[158:159]
	s_waitcnt lgkmcnt(0)
	global_store_dwordx4 v[168:169], v[154:157], off
	s_nop 1
	v_cvt_pk_bf16_f32 v154, v86, v87
	v_cvt_pk_bf16_f32 v155, v88, v89
	v_cvt_pk_bf16_f32 v156, v82, v83
	v_cvt_pk_bf16_f32 v157, v84, v85
	ds_bpermute_b32 v154, v164, v154
	ds_bpermute_b32 v155, v164, v155
	ds_bpermute_b32 v156, v164, v156
	ds_bpermute_b32 v157, v164, v157
	v_lshl_add_u64 v[168:169], v[166:167], 0, v[158:159]
	s_waitcnt lgkmcnt(0)
	global_store_dwordx4 v[168:169], v[154:157], off offset:256
	v_add_co_u32_e32 v158, vcc, s48, v150
	s_nop 0
	v_cvt_pk_bf16_f32 v154, v78, v79
	v_cvt_pk_bf16_f32 v155, v80, v81
	v_cvt_pk_bf16_f32 v156, v74, v75
	v_cvt_pk_bf16_f32 v157, v76, v77
	s_nop 0
	v_addc_co_u32_e32 v159, vcc, 0, v151, vcc
	ds_bpermute_b32 v154, v164, v154
	ds_bpermute_b32 v155, v164, v155
	ds_bpermute_b32 v156, v164, v156
	ds_bpermute_b32 v157, v164, v157
	v_lshl_add_u64 v[168:169], v[166:167], 0, v[158:159]
	s_waitcnt lgkmcnt(0)
	global_store_dwordx4 v[168:169], v[154:157], off
	s_nop 1
	v_cvt_pk_bf16_f32 v154, v70, v71
	v_cvt_pk_bf16_f32 v155, v72, v73
	v_cvt_pk_bf16_f32 v156, v66, v67
	v_cvt_pk_bf16_f32 v157, v68, v69
	ds_bpermute_b32 v154, v164, v154
	ds_bpermute_b32 v155, v164, v155
	ds_bpermute_b32 v156, v164, v156
	ds_bpermute_b32 v157, v164, v157
	v_lshl_add_u64 v[168:169], v[166:167], 0, v[158:159]
	s_waitcnt lgkmcnt(0)
	global_store_dwordx4 v[168:169], v[154:157], off offset:256
	v_add_co_u32_e32 v158, vcc, s42, v150
	s_nop 0
	v_cvt_pk_bf16_f32 v154, v62, v63
	v_cvt_pk_bf16_f32 v155, v64, v65
	v_cvt_pk_bf16_f32 v156, v58, v59
	v_cvt_pk_bf16_f32 v157, v60, v61
	s_nop 0
	v_addc_co_u32_e32 v159, vcc, 0, v151, vcc
	ds_bpermute_b32 v154, v164, v154
	ds_bpermute_b32 v155, v164, v155
	ds_bpermute_b32 v156, v164, v156
	ds_bpermute_b32 v157, v164, v157
	v_lshl_add_u64 v[168:169], v[166:167], 0, v[158:159]
	s_waitcnt lgkmcnt(0)
	global_store_dwordx4 v[168:169], v[154:157], off
	s_nop 1
	v_cvt_pk_bf16_f32 v154, v54, v55
	v_cvt_pk_bf16_f32 v155, v56, v57
	v_cvt_pk_bf16_f32 v156, v50, v51
	v_cvt_pk_bf16_f32 v157, v52, v53
	ds_bpermute_b32 v154, v164, v154
	ds_bpermute_b32 v155, v164, v155
	ds_bpermute_b32 v156, v164, v156
	ds_bpermute_b32 v157, v164, v157
	v_lshl_add_u64 v[168:169], v[166:167], 0, v[158:159]
	s_waitcnt lgkmcnt(0)
	global_store_dwordx4 v[168:169], v[154:157], off offset:256
	v_add_co_u32_e32 v158, vcc, s43, v150
	s_nop 0
	v_cvt_pk_bf16_f32 v154, v46, v47
	v_cvt_pk_bf16_f32 v155, v48, v49
	v_cvt_pk_bf16_f32 v156, v42, v43
	v_cvt_pk_bf16_f32 v157, v44, v45
	s_nop 0
	v_addc_co_u32_e32 v159, vcc, 0, v151, vcc
	ds_bpermute_b32 v154, v164, v154
	ds_bpermute_b32 v155, v164, v155
	ds_bpermute_b32 v156, v164, v156
	ds_bpermute_b32 v157, v164, v157
	v_lshl_add_u64 v[168:169], v[166:167], 0, v[158:159]
	s_waitcnt lgkmcnt(0)
	global_store_dwordx4 v[168:169], v[154:157], off
	s_nop 1
	v_cvt_pk_bf16_f32 v154, v38, v39
	v_cvt_pk_bf16_f32 v155, v40, v41
	v_cvt_pk_bf16_f32 v156, v34, v35
	v_cvt_pk_bf16_f32 v157, v36, v37
	ds_bpermute_b32 v154, v164, v154
	ds_bpermute_b32 v155, v164, v155
	ds_bpermute_b32 v156, v164, v156
	ds_bpermute_b32 v157, v164, v157
	v_lshl_add_u64 v[168:169], v[166:167], 0, v[158:159]
	s_waitcnt lgkmcnt(0)
	global_store_dwordx4 v[168:169], v[154:157], off offset:256
	v_add_co_u32_e32 v158, vcc, s44, v150
	s_nop 0
	v_cvt_pk_bf16_f32 v154, v30, v31
	v_cvt_pk_bf16_f32 v155, v32, v33
	v_cvt_pk_bf16_f32 v156, v26, v27
	v_cvt_pk_bf16_f32 v157, v28, v29
	s_nop 0
	v_addc_co_u32_e32 v159, vcc, 0, v151, vcc
	ds_bpermute_b32 v154, v164, v154
	ds_bpermute_b32 v155, v164, v155
	ds_bpermute_b32 v156, v164, v156
	ds_bpermute_b32 v157, v164, v157
	v_lshl_add_u64 v[168:169], v[166:167], 0, v[158:159]
	s_waitcnt lgkmcnt(0)
	global_store_dwordx4 v[168:169], v[154:157], off
	v_add_co_u32_e32 v150, vcc, s45, v150
	s_nop 0
	v_cvt_pk_bf16_f32 v154, v22, v23
	v_cvt_pk_bf16_f32 v155, v24, v25
	v_cvt_pk_bf16_f32 v156, v18, v19
	v_cvt_pk_bf16_f32 v157, v20, v21
	ds_bpermute_b32 v154, v164, v154
	ds_bpermute_b32 v155, v164, v155
	ds_bpermute_b32 v156, v164, v156
	ds_bpermute_b32 v157, v164, v157
	v_lshl_add_u64 v[168:169], v[166:167], 0, v[158:159]
	s_waitcnt lgkmcnt(0)
	global_store_dwordx4 v[168:169], v[154:157], off offset:256
	v_addc_co_u32_e32 v151, vcc, 0, v151, vcc
	s_nop 0
	v_cvt_pk_bf16_f32 v154, v14, v15
	v_cvt_pk_bf16_f32 v155, v16, v17
	v_cvt_pk_bf16_f32 v156, v10, v11
	v_cvt_pk_bf16_f32 v157, v12, v13
	ds_bpermute_b32 v154, v164, v154
	ds_bpermute_b32 v155, v164, v155
	ds_bpermute_b32 v156, v164, v156
	ds_bpermute_b32 v157, v164, v157
	v_lshl_add_u64 v[168:169], v[166:167], 0, v[150:151]
	s_waitcnt lgkmcnt(0)
	global_store_dwordx4 v[168:169], v[154:157], off
	s_nop 1
	v_cvt_pk_bf16_f32 v154, v6, v7
	v_cvt_pk_bf16_f32 v155, v8, v9
	v_cvt_pk_bf16_f32 v156, v2, v3
	v_cvt_pk_bf16_f32 v157, v4, v5
	ds_bpermute_b32 v154, v164, v154
	ds_bpermute_b32 v155, v164, v155
	ds_bpermute_b32 v156, v164, v156
	ds_bpermute_b32 v157, v164, v157
	v_lshl_add_u64 v[168:169], v[166:167], 0, v[150:151]
	s_waitcnt lgkmcnt(0)
	global_store_dwordx4 v[168:169], v[154:157], off offset:256
.LBB0_934:
	s_andn2_b64 vcc, exec, s[22:23]
	s_cbranch_vccnz .LBB0_924
	v_and_b32_e32 v165, 3, v174
	v_lshrrev_b32_e32 v170, 2, v174
	v_lshlrev_b32_e32 v164, 6, v165
	v_and_or_b32 v164, v174, 60, v164
	v_and_b32_e32 v171, 15, v174
	v_sub_u32_e32 v170, v170, v171
	v_lshrrev_b32_e32 v171, 4, v174
	v_sub_u32_e32 v165, v165, v171
	v_mul_i32_i24_e32 v170, 0x2000, v170
	v_lshl_add_u32 v166, v165, 4, v170
	v_ashrrev_i32_e32 v167, 31, v166
	v_lshl_add_u32 v154, s66, 8, v140
	v_lshl_or_b32 v150, s65, 8, v135
	v_ashrrev_i32_e32 v155, 31, v154
	v_ashrrev_i32_e32 v151, 31, v150
	v_lshlrev_b64 v[156:157], 13, v[154:155]
	v_lshl_add_u64 v[156:157], s[4:5], 0, v[156:157]
	v_lshlrev_b64 v[158:159], 1, v[150:151]
	v_lshl_add_u64 v[150:151], v[156:157], 0, v[158:159]
	v_cvt_pk_bf16_f32 v126, v126, v127
	v_cvt_pk_bf16_f32 v127, v128, v129
	v_cvt_pk_bf16_f32 v128, v122, v123
	v_cvt_pk_bf16_f32 v129, v124, v125
	ds_bpermute_b32 v126, v164, v126
	ds_bpermute_b32 v127, v164, v127
	ds_bpermute_b32 v128, v164, v128
	ds_bpermute_b32 v129, v164, v129
	v_lshl_add_u64 v[168:169], v[166:167], 0, v[150:151]
	s_waitcnt lgkmcnt(0)
	global_store_dwordx4 v[168:169], v[126:129], off
	v_cvt_pk_bf16_f32 v118, v118, v119
	v_cvt_pk_bf16_f32 v119, v120, v121
	v_cvt_pk_bf16_f32 v120, v114, v115
	v_or_b32_e32 v114, 16, v154
	v_ashrrev_i32_e32 v115, 31, v114
	v_lshlrev_b64 v[114:115], 13, v[114:115]
	v_lshl_add_u64 v[114:115], s[4:5], 0, v[114:115]
	v_lshl_add_u64 v[114:115], v[114:115], 0, v[158:159]
	v_cvt_pk_bf16_f32 v121, v116, v117
	ds_bpermute_b32 v118, v164, v118
	ds_bpermute_b32 v119, v164, v119
	ds_bpermute_b32 v120, v164, v120
	ds_bpermute_b32 v121, v164, v121
	v_lshl_add_u64 v[168:169], v[166:167], 0, v[150:151]
	s_waitcnt lgkmcnt(0)
	global_store_dwordx4 v[168:169], v[118:121], off offset:256
	v_cvt_pk_bf16_f32 v110, v110, v111
	v_cvt_pk_bf16_f32 v111, v112, v113
	v_cvt_pk_bf16_f32 v112, v106, v107
	v_cvt_pk_bf16_f32 v113, v108, v109
	ds_bpermute_b32 v110, v164, v110
	ds_bpermute_b32 v111, v164, v111
	ds_bpermute_b32 v112, v164, v112
	ds_bpermute_b32 v113, v164, v113
	v_lshl_add_u64 v[168:169], v[166:167], 0, v[114:115]
	s_waitcnt lgkmcnt(0)
	global_store_dwordx4 v[168:169], v[110:113], off
	v_cvt_pk_bf16_f32 v102, v102, v103
	v_cvt_pk_bf16_f32 v103, v104, v105
	v_cvt_pk_bf16_f32 v104, v98, v99
	v_or_b32_e32 v98, 32, v154
	v_ashrrev_i32_e32 v99, 31, v98
	v_lshlrev_b64 v[98:99], 13, v[98:99]
	v_lshl_add_u64 v[98:99], s[4:5], 0, v[98:99]
	v_lshl_add_u64 v[98:99], v[98:99], 0, v[158:159]
	v_cvt_pk_bf16_f32 v105, v100, v101
	ds_bpermute_b32 v102, v164, v102
	ds_bpermute_b32 v103, v164, v103
	ds_bpermute_b32 v104, v164, v104
	ds_bpermute_b32 v105, v164, v105
	v_lshl_add_u64 v[168:169], v[166:167], 0, v[114:115]
	s_waitcnt lgkmcnt(0)
	global_store_dwordx4 v[168:169], v[102:105], off offset:256
	v_cvt_pk_bf16_f32 v94, v94, v95
	v_cvt_pk_bf16_f32 v95, v96, v97
	v_cvt_pk_bf16_f32 v96, v90, v91
	v_cvt_pk_bf16_f32 v97, v92, v93
	ds_bpermute_b32 v94, v164, v94
	ds_bpermute_b32 v95, v164, v95
	ds_bpermute_b32 v96, v164, v96
	ds_bpermute_b32 v97, v164, v97
	v_lshl_add_u64 v[168:169], v[166:167], 0, v[98:99]
	s_waitcnt lgkmcnt(0)
	global_store_dwordx4 v[168:169], v[94:97], off
	v_cvt_pk_bf16_f32 v86, v86, v87
	v_cvt_pk_bf16_f32 v87, v88, v89
	v_cvt_pk_bf16_f32 v88, v82, v83
	v_or_b32_e32 v82, 48, v154
	v_ashrrev_i32_e32 v83, 31, v82
	v_lshlrev_b64 v[82:83], 13, v[82:83]
	v_lshl_add_u64 v[82:83], s[4:5], 0, v[82:83]
	v_lshl_add_u64 v[82:83], v[82:83], 0, v[158:159]
	v_cvt_pk_bf16_f32 v89, v84, v85
	ds_bpermute_b32 v86, v164, v86
	ds_bpermute_b32 v87, v164, v87
	ds_bpermute_b32 v88, v164, v88
	ds_bpermute_b32 v89, v164, v89
	v_lshl_add_u64 v[168:169], v[166:167], 0, v[98:99]
	s_waitcnt lgkmcnt(0)
	global_store_dwordx4 v[168:169], v[86:89], off offset:256
	v_cvt_pk_bf16_f32 v78, v78, v79
	v_cvt_pk_bf16_f32 v79, v80, v81
	v_cvt_pk_bf16_f32 v80, v74, v75
	v_cvt_pk_bf16_f32 v81, v76, v77
	ds_bpermute_b32 v78, v164, v78
	ds_bpermute_b32 v79, v164, v79
	ds_bpermute_b32 v80, v164, v80
	ds_bpermute_b32 v81, v164, v81
	v_lshl_add_u64 v[168:169], v[166:167], 0, v[82:83]
	s_waitcnt lgkmcnt(0)
	global_store_dwordx4 v[168:169], v[78:81], off
	v_cvt_pk_bf16_f32 v70, v70, v71
	v_cvt_pk_bf16_f32 v71, v72, v73
	v_cvt_pk_bf16_f32 v72, v66, v67
	v_cvt_pk_bf16_f32 v73, v68, v69
	ds_bpermute_b32 v70, v164, v70
	ds_bpermute_b32 v71, v164, v71
	ds_bpermute_b32 v72, v164, v72
	ds_bpermute_b32 v73, v164, v73
	v_lshl_add_u64 v[168:169], v[166:167], 0, v[82:83]
	s_waitcnt lgkmcnt(0)
	global_store_dwordx4 v[168:169], v[70:73], off offset:256
	v_cvt_pk_bf16_f32 v62, v62, v63
	v_cvt_pk_bf16_f32 v63, v64, v65
	v_cvt_pk_bf16_f32 v64, v58, v59
	v_add_co_u32_e32 v58, vcc, s59, v150
	v_lshl_add_u64 v[66:67], v[150:151], 0, s[8:9]
	s_nop 0
	v_addc_co_u32_e32 v59, vcc, 0, v151, vcc
	v_cvt_pk_bf16_f32 v65, v60, v61
	ds_bpermute_b32 v62, v164, v62
	ds_bpermute_b32 v63, v164, v63
	ds_bpermute_b32 v64, v164, v64
	ds_bpermute_b32 v65, v164, v65
	v_lshl_add_u64 v[168:169], v[166:167], 0, v[58:59]
	s_waitcnt lgkmcnt(0)
	global_store_dwordx4 v[168:169], v[62:65], off
	v_cvt_pk_bf16_f32 v54, v54, v55
	v_cvt_pk_bf16_f32 v55, v56, v57
	v_cvt_pk_bf16_f32 v56, v50, v51
	v_cvt_pk_bf16_f32 v57, v52, v53
	ds_bpermute_b32 v54, v164, v54
	ds_bpermute_b32 v55, v164, v55
	ds_bpermute_b32 v56, v164, v56
	ds_bpermute_b32 v57, v164, v57
	v_lshl_add_u64 v[168:169], v[166:167], 0, v[66:67]
	s_waitcnt lgkmcnt(0)
	global_store_dwordx4 v[168:169], v[54:57], off offset:256
	v_cvt_pk_bf16_f32 v46, v46, v47
	v_cvt_pk_bf16_f32 v47, v48, v49
	v_cvt_pk_bf16_f32 v48, v42, v43
	v_add_co_u32_e32 v42, vcc, s60, v150
	v_lshl_add_u64 v[50:51], v[150:151], 0, s[10:11]
	s_nop 0
	v_addc_co_u32_e32 v43, vcc, 0, v151, vcc
	v_cvt_pk_bf16_f32 v49, v44, v45
	ds_bpermute_b32 v46, v164, v46
	ds_bpermute_b32 v47, v164, v47
	ds_bpermute_b32 v48, v164, v48
	ds_bpermute_b32 v49, v164, v49
	v_lshl_add_u64 v[168:169], v[166:167], 0, v[42:43]
	s_waitcnt lgkmcnt(0)
	global_store_dwordx4 v[168:169], v[46:49], off
	v_cvt_pk_bf16_f32 v38, v38, v39
	v_cvt_pk_bf16_f32 v39, v40, v41
	v_cvt_pk_bf16_f32 v40, v34, v35
	v_cvt_pk_bf16_f32 v41, v36, v37
	ds_bpermute_b32 v38, v164, v38
	ds_bpermute_b32 v39, v164, v39
	ds_bpermute_b32 v40, v164, v40
	ds_bpermute_b32 v41, v164, v41
	v_lshl_add_u64 v[168:169], v[166:167], 0, v[50:51]
	s_waitcnt lgkmcnt(0)
	global_store_dwordx4 v[168:169], v[38:41], off offset:256
	v_cvt_pk_bf16_f32 v30, v30, v31
	v_cvt_pk_bf16_f32 v31, v32, v33
	v_cvt_pk_bf16_f32 v32, v26, v27
	v_add_co_u32_e32 v26, vcc, s61, v150
	v_lshl_add_u64 v[34:35], v[150:151], 0, s[12:13]
	s_nop 0
	v_addc_co_u32_e32 v27, vcc, 0, v151, vcc
	v_cvt_pk_bf16_f32 v33, v28, v29
	ds_bpermute_b32 v30, v164, v30
	ds_bpermute_b32 v31, v164, v31
	ds_bpermute_b32 v32, v164, v32
	ds_bpermute_b32 v33, v164, v33
	v_lshl_add_u64 v[168:169], v[166:167], 0, v[26:27]
	s_waitcnt lgkmcnt(0)
	global_store_dwordx4 v[168:169], v[30:33], off
	v_cvt_pk_bf16_f32 v22, v22, v23
	v_cvt_pk_bf16_f32 v23, v24, v25
	v_cvt_pk_bf16_f32 v24, v18, v19
	v_cvt_pk_bf16_f32 v25, v20, v21
	ds_bpermute_b32 v22, v164, v22
	ds_bpermute_b32 v23, v164, v23
	ds_bpermute_b32 v24, v164, v24
	ds_bpermute_b32 v25, v164, v25
	v_lshl_add_u64 v[168:169], v[166:167], 0, v[34:35]
	s_waitcnt lgkmcnt(0)
	global_store_dwordx4 v[168:169], v[22:25], off offset:256
	v_cvt_pk_bf16_f32 v14, v14, v15
	v_cvt_pk_bf16_f32 v15, v16, v17
	v_cvt_pk_bf16_f32 v16, v10, v11
	v_add_co_u32_e32 v10, vcc, s62, v150
	v_lshl_add_u64 v[18:19], v[150:151], 0, s[14:15]
	s_nop 0
	v_addc_co_u32_e32 v11, vcc, 0, v151, vcc
	v_cvt_pk_bf16_f32 v17, v12, v13
	ds_bpermute_b32 v14, v164, v14
	ds_bpermute_b32 v15, v164, v15
	ds_bpermute_b32 v16, v164, v16
	ds_bpermute_b32 v17, v164, v17
	v_lshl_add_u64 v[168:169], v[166:167], 0, v[10:11]
	s_waitcnt lgkmcnt(0)
	global_store_dwordx4 v[168:169], v[14:17], off
	v_cvt_pk_bf16_f32 v6, v6, v7
	v_cvt_pk_bf16_f32 v7, v8, v9
	v_cvt_pk_bf16_f32 v8, v2, v3
	v_cvt_pk_bf16_f32 v9, v4, v5
	ds_bpermute_b32 v6, v164, v6
	ds_bpermute_b32 v7, v164, v7
	ds_bpermute_b32 v8, v164, v8
	ds_bpermute_b32 v9, v164, v9
	v_lshl_add_u64 v[168:169], v[166:167], 0, v[18:19]
	s_waitcnt lgkmcnt(0)
	global_store_dwordx4 v[168:169], v[6:9], off offset:256
	s_branch .LBB0_924
